# v10 plus one static s_setprio 1 for waves 0-3 at the start of the attention phase (GEMM phases keep their own per-block priorities)
# baseline (speedup 1.0000x reference)
.LBB0_1089:
	s_or_b64 exec, exec, s[0:1]
	v_readlane_b32 s2, v253, 0
	s_lshl_b32 s0, s2, 5
	s_ashr_i32 s23, s2, 3
	s_and_b32 s18, s0, 0xe0
	s_add_i32 s18, s18, s23
	s_and_b64 s[0:1], s[86:87], exec
	s_cselect_b32 s68, s18, s2
	s_cmpk_lt_i32 s68, 0x610
	s_cselect_b64 s[2:3], -1, 0
	s_cmpk_gt_i32 s68, 0x60f
	s_waitcnt lgkmcnt(0)
	s_barrier
	s_cselect_b32 s99, 1, 0
	v_readfirstlane_b32 s98, v0
	s_nop 3
	s_and_b32 s98, s98, 0x3ff
	s_lshr_b32 s98, s98, 6
	s_cmp_ge_u32 s98, 4
	s_cbranch_scc1 .Lprio_att_done
	s_setprio 1
.Lprio_att_done:
	s_cmp_lg_u32 s99, 0
	s_cbranch_scc1 .LBB0_1092
	s_cmpk_gt_i32 s68, 0x40f
	s_cselect_b64 s[36:37], -1, 0
	s_cmpk_lt_i32 s68, 0x410
	s_cselect_b64 s[20:21], -1, 0
	s_and_b64 vcc, exec, s[36:37]
	s_cbranch_vccnz .LBB0_1093
	s_mul_hi_i32 s0, s68, 0x7e07e07f
	s_lshr_b32 s1, s0, 31
	s_ashr_i32 s0, s0, 7
	s_add_i32 s4, s0, s1
	s_mul_i32 s0, s4, 0xfffffefc
	s_add_i32 s0, s0, s68
	s_mul_hi_i32 s1, s0, 0x7e07e07f
	s_lshr_b32 s5, s1, 31
	s_ashr_i32 s1, s1, 5
	s_add_i32 s10, s1, s5
	s_mul_i32 s1, s10, 0xffffffbf
	s_add_i32 s1, s1, s0
	s_lshl_b32 s0, s1, 5
	s_add_i32 s19, s0, 0xffffff80
	s_cbranch_execz .LBB0_1094
	s_branch .LBB0_1095
